# retention-latent attention unit: LDS fragment reads hoisted ahead of their MFMAs into free VGPRs (up to 8 in flight), lgkmcnt waits recounted
# speedup vs baseline: 1.0337x; 1.0030x over previous
.LBB0_1153:
	s_waitcnt lgkmcnt(0)
	ds_read_b64_tr_b16 v[150:151], v203 offset:57600
	ds_read_b64_tr_b16 v[148:149], v203 offset:55296
	ds_read_b64_tr_b16 v[152:153], v203 offset:55328
	ds_read_b64_tr_b16 v[154:155], v203 offset:57632
	ds_read_b64_tr_b16 v[156:157], v203 offset:55360
	ds_read_b64_tr_b16 v[158:159], v203 offset:57664
	ds_read_b64_tr_b16 v[160:161], v203 offset:55392
	ds_read_b64_tr_b16 v[162:163], v203 offset:57696
	v_cvt_pk_bf16_f32 v112, v36, v37
	v_cvt_pk_bf16_f32 v40, v40, v41
	v_cvt_pk_bf16_f32 v41, v42, v43
	v_cvt_pk_bf16_f32 v42, v44, v45
	v_cvt_pk_bf16_f32 v43, v46, v47
	v_cvt_pk_bf16_f32 v36, v48, v49
	v_cvt_pk_bf16_f32 v37, v50, v51
	s_nop 0
	s_nop 0
	s_nop 0
	s_nop 0
	v_cvt_pk_bf16_f32 v110, v32, v33
	v_cvt_pk_bf16_f32 v111, v34, v35
	v_cvt_pk_bf16_f32 v113, v38, v39
	v_cvt_pk_bf16_f32 v38, v52, v53
	v_cvt_pk_bf16_f32 v39, v54, v55
	v_cvt_pk_bf16_f32 v32, v56, v57
	v_cvt_pk_bf16_f32 v33, v58, v59
	v_cvt_pk_bf16_f32 v34, v60, v61
	v_cvt_pk_bf16_f32 v35, v62, v63
	s_nop 0
	s_nop 0
	s_nop 0
	s_nop 0
	ds_read_b64_tr_b16 v[164:165], v203 offset:59904
	ds_read_b64_tr_b16 v[166:167], v203 offset:62208
	s_nop 0
	s_waitcnt lgkmcnt(8)
	v_mfma_f32_16x16x32_bf16 v[44:47], v[148:151], v[110:113], v[126:129]
	s_nop 0
	s_waitcnt lgkmcnt(0)
	v_mfma_f32_16x16x32_bf16 v[44:47], v[164:167], v[40:43], v[44:47]
	ds_read_b64_tr_b16 v[148:149], v203 offset:59936
	ds_read_b64_tr_b16 v[150:151], v203 offset:62240
	v_mfma_f32_16x16x32_bf16 v[48:51], v[152:155], v[110:113], v[130:133]
	ds_read_b64_tr_b16 v[152:153], v203 offset:59968
	ds_read_b64_tr_b16 v[154:155], v203 offset:62272
	s_nop 0
	s_waitcnt lgkmcnt(2)
	v_mfma_f32_16x16x32_bf16 v[48:51], v[148:151], v[40:43], v[48:51]
	s_nop 0
	s_nop 0
	ds_read_b64_tr_b16 v[148:149], v203 offset:64512
	ds_read_b64_tr_b16 v[150:151], v219 offset:11520
	v_mfma_f32_16x16x32_bf16 v[52:55], v[156:159], v[110:113], v[134:137]
	ds_read_b64_tr_b16 v[156:157], v203 offset:64576
	ds_read_b64_tr_b16 v[158:159], v219 offset:11584
	s_nop 0
	s_waitcnt lgkmcnt(4)
	v_mfma_f32_16x16x32_bf16 v[52:55], v[152:155], v[40:43], v[52:55]
	ds_read_b64_tr_b16 v[152:153], v219 offset:13824
	ds_read_b64_tr_b16 v[154:155], v219 offset:16128
	ds_read_b64_tr_b16 v[60:61], v203 offset:60000
	ds_read_b64_tr_b16 v[62:63], v203 offset:62304
	v_mfma_f32_16x16x32_bf16 v[56:59], v[160:163], v[110:113], v[138:141]
	ds_read_b64_tr_b16 v[160:161], v219 offset:13856
	ds_read_b64_tr_b16 v[162:163], v219 offset:16160
	s_nop 0
	s_waitcnt lgkmcnt(2)
	v_mfma_f32_16x16x32_bf16 v[40:43], v[60:63], v[40:43], v[56:59]
	s_nop 5
	s_nop 0
	s_nop 0
	ds_read_b64_tr_b16 v[60:61], v219 offset:11552
	s_nop 0
	v_mfma_f32_16x16x32_bf16 v[44:47], v[148:151], v[36:39], v[44:47]
	ds_read_b64_tr_b16 v[148:149], v219 offset:13888
	ds_read_b64_tr_b16 v[150:151], v219 offset:16192
	ds_read_b64_tr_b16 v[58:59], v203 offset:64544
	s_nop 0
	s_waitcnt lgkmcnt(0)
	v_mfma_f32_16x16x32_bf16 v[48:51], v[58:61], v[36:39], v[48:51]
	s_nop 0
	s_nop 0
	s_nop 0
	v_mfma_f32_16x16x32_bf16 v[52:55], v[156:159], v[36:39], v[52:55]
	ds_read_b64_tr_b16 v[56:57], v203 offset:64608
	ds_read_b64_tr_b16 v[58:59], v219 offset:11616
	s_nop 0
	s_waitcnt lgkmcnt(0)
	v_mfma_f32_16x16x32_bf16 v[36:39], v[56:59], v[36:39], v[40:43]
	s_nop 2
	s_nop 0
	s_nop 0
	s_nop 0
	v_mfma_f32_16x16x32_bf16 v[118:121], v[152:155], v[32:35], v[44:47]
	s_nop 0
	s_nop 0
	s_nop 0
	v_mfma_f32_16x16x32_bf16 v[122:125], v[160:163], v[32:35], v[48:51]
	s_nop 0
	s_nop 0
	s_nop 0
	v_mfma_f32_16x16x32_bf16 v[114:117], v[148:151], v[32:35], v[52:55]
	ds_read_b64_tr_b16 v[40:41], v219 offset:13920
	ds_read_b64_tr_b16 v[42:43], v219 offset:16224
	s_nop 0
	s_waitcnt lgkmcnt(0)
	v_mfma_f32_16x16x32_bf16 v[110:113], v[40:43], v[32:35], v[36:39]

.LBB0_1164:
	s_mov_b64 s[6:7], -1
	s_and_b64 vcc, exec, s[10:11]
	s_cbranch_vccz .LBB0_1166
	s_waitcnt lgkmcnt(0)
	ds_read_b128 v[148:151], v223
	ds_read_b128 v[152:155], v223 offset:64
	ds_read_b128 v[156:159], v223 offset:2304
	ds_read_b128 v[160:163], v223 offset:2368
	ds_read_b128 v[164:167], v223 offset:4608
	ds_read_b128 v[168:171], v223 offset:4672
	ds_read_b128 v[240:243], v223 offset:6912
	ds_read_b128 v[244:247], v223 offset:6976
	s_cmpk_eq_i32 s19, 0x400
	s_cselect_b64 vcc, -1, 0
	v_cndmask_b32_e32 v52, v178, v201, vcc
	s_nop 0
	s_waitcnt lgkmcnt(7)
	v_mfma_f32_16x16x32_bf16 v[32:35], v[148:151], v[66:69], 0
	ds_read_b64_tr_b16 v[150:151], v203 offset:20736
	s_mov_b64 s[6:7], 0
	s_nop 0
	s_waitcnt lgkmcnt(7)
	v_mfma_f32_16x16x32_bf16 v[32:35], v[152:155], v[70:73], v[32:35]
	s_nop 0
	s_nop 0
	ds_read_b64_tr_b16 v[148:149], v203 offset:18432
	s_nop 0
	s_waitcnt lgkmcnt(7)
	v_mfma_f32_16x16x32_bf16 v[36:39], v[156:159], v[66:69], 0
	ds_read_b64_tr_b16 v[152:153], v203 offset:18464
	s_nop 3
	v_mul_f32_e64 v32, v52, v32
	v_mul_f32_e64 v33, v52, v33
	v_pk_mul_f32 v[34:35], v[52:53], v[34:35] op_sel_hi:[0,1]
	v_cvt_pk_bf16_f32 v32, v32, v33
	s_nop 0
	s_waitcnt lgkmcnt(7)
	v_mfma_f32_16x16x32_bf16 v[36:39], v[160:163], v[70:73], v[36:39]
	s_nop 0
	s_nop 0
	ds_read_b64_tr_b16 v[154:155], v203 offset:20768
	v_cvt_pk_bf16_f32 v33, v34, v35
	s_nop 0
	s_waitcnt lgkmcnt(7)
	v_mfma_f32_16x16x32_bf16 v[40:43], v[164:167], v[66:69], 0
	ds_read_b64_tr_b16 v[156:157], v203 offset:18496
	s_nop 2
	v_mul_f32_e64 v36, v52, v36
	v_mul_f32_e64 v37, v52, v37
	v_pk_mul_f32 v[38:39], v[52:53], v[38:39] op_sel_hi:[0,1]
	v_cvt_pk_bf16_f32 v34, v36, v37
	s_nop 0
	s_waitcnt lgkmcnt(7)
	v_mfma_f32_16x16x32_bf16 v[40:43], v[168:171], v[70:73], v[40:43]
	s_nop 0
	s_nop 0
	ds_read_b64_tr_b16 v[158:159], v203 offset:20800
	v_cvt_pk_bf16_f32 v35, v38, v39
	s_nop 0
	s_waitcnt lgkmcnt(7)
	v_mfma_f32_16x16x32_bf16 v[44:47], v[240:243], v[66:69], 0
	ds_read_b64_tr_b16 v[160:161], v203 offset:18528
	s_nop 2
	v_mul_f32_e64 v40, v52, v40
	v_mul_f32_e64 v41, v52, v41
	v_pk_mul_f32 v[42:43], v[52:53], v[42:43] op_sel_hi:[0,1]
	v_cvt_pk_bf16_f32 v36, v40, v41
	s_nop 0
	s_waitcnt lgkmcnt(7)
	v_mfma_f32_16x16x32_bf16 v[44:47], v[244:247], v[70:73], v[44:47]
	ds_read_b64_tr_b16 v[162:163], v203 offset:20832
	v_cvt_pk_bf16_f32 v37, v42, v43
	s_nop 6
	v_pk_mul_f32 v[44:45], v[52:53], v[44:45] op_sel_hi:[0,1]
	v_pk_mul_f32 v[46:47], v[52:53], v[46:47] op_sel_hi:[0,1]
	v_cvt_pk_bf16_f32 v38, v44, v45
	v_cvt_pk_bf16_f32 v39, v46, v47
	s_nop 0
	s_nop 0
	s_nop 0
	s_nop 0
	s_nop 0
	s_nop 0
	s_nop 0
	s_nop 0
	s_nop 0
	s_waitcnt lgkmcnt(6)
	v_mfma_f32_16x16x32_bf16 v[40:43], v[148:151], v[32:35], v[118:121]
	ds_read_b64_tr_b16 v[148:149], v203 offset:23072
	ds_read_b64_tr_b16 v[150:151], v203 offset:25376
	s_nop 0
	s_waitcnt lgkmcnt(6)
	v_mfma_f32_16x16x32_bf16 v[44:47], v[152:155], v[32:35], v[122:125]
	ds_read_b64_tr_b16 v[152:153], v203 offset:23104
	ds_read_b64_tr_b16 v[154:155], v203 offset:25408
	s_nop 0
	s_waitcnt lgkmcnt(6)
	v_mfma_f32_16x16x32_bf16 v[48:51], v[156:159], v[32:35], v[114:117]
	s_nop 0
	s_waitcnt lgkmcnt(4)
	v_mfma_f32_16x16x32_bf16 v[32:35], v[160:163], v[32:35], v[110:113]
	ds_read_b64_tr_b16 v[52:53], v203 offset:23040
	ds_read_b64_tr_b16 v[54:55], v203 offset:25344
	s_nop 0
	s_waitcnt lgkmcnt(0)
	v_mfma_f32_16x16x32_bf16 v[126:129], v[52:55], v[36:39], v[40:43]
	s_nop 2
	s_nop 0
	s_nop 0
	s_nop 0
	v_mfma_f32_16x16x32_bf16 v[130:133], v[148:151], v[36:39], v[44:47]
	s_nop 0
	s_nop 0
	s_nop 0
	v_mfma_f32_16x16x32_bf16 v[134:137], v[152:155], v[36:39], v[48:51]
	ds_read_b64_tr_b16 v[40:41], v203 offset:23136
	ds_read_b64_tr_b16 v[42:43], v203 offset:25440
	s_nop 0
	s_waitcnt lgkmcnt(0)
	v_mfma_f32_16x16x32_bf16 v[138:141], v[40:43], v[36:39], v[32:35]
.LBB0_1166:
	s_andn2_b64 vcc, exec, s[6:7]
	s_cbranch_vccnz .LBB0_1176
	s_waitcnt lgkmcnt(0)
	ds_read_b128 v[160:163], v223
	ds_read_b128 v[164:167], v223 offset:64
	ds_read_b128 v[168:171], v223 offset:2304
	ds_read_b128 v[240:243], v223 offset:2368
	ds_read_b128 v[244:247], v223 offset:4608
	ds_read_b128 v[248:251], v223 offset:4672
	s_nop 0
	v_cvt_f32_i32_e32 v32, v224
	s_add_i32 s20, s19, 0x7f
	v_readfirstlane_b32 s9, v186
	s_mov_b64 s[6:7], -1
	v_mul_f32_e32 v40, v187, v32
	s_nop 0
	s_nop 0
	v_exp_f32_e32 v64, v40
	s_cmp_ge_i32 s20, s9
	s_nop 0
	s_waitcnt lgkmcnt(5)
	v_mfma_f32_16x16x32_bf16 v[32:35], v[160:163], v[66:69], 0
	ds_read_b128 v[160:163], v223 offset:6912
	s_nop 0
	s_waitcnt lgkmcnt(5)
	v_mfma_f32_16x16x32_bf16 v[126:129], v[164:167], v[70:73], v[32:35]
	ds_read_b128 v[164:167], v223 offset:6976
	s_nop 5
	s_nop 0
	s_nop 0
	s_nop 0
	s_waitcnt lgkmcnt(5)
	v_mfma_f32_16x16x32_bf16 v[32:35], v[168:171], v[66:69], 0
	ds_read_b128 v[168:171], v223 offset:9216
	s_nop 0
	s_waitcnt lgkmcnt(5)
	v_mfma_f32_16x16x32_bf16 v[130:133], v[240:243], v[70:73], v[32:35]
	ds_read_b128 v[240:243], v223 offset:9280
	s_nop 5
	s_nop 0
	s_nop 0
	s_nop 0
	s_waitcnt lgkmcnt(5)
	v_mfma_f32_16x16x32_bf16 v[32:35], v[244:247], v[66:69], 0
	ds_read_b128 v[244:247], v223 offset:11520
	s_nop 0
	s_waitcnt lgkmcnt(5)
	v_mfma_f32_16x16x32_bf16 v[134:137], v[248:251], v[70:73], v[32:35]
	ds_read_b128 v[248:251], v223 offset:11584
	s_nop 5
	s_nop 0
	s_nop 0
	s_nop 0
	s_waitcnt lgkmcnt(5)
	v_mfma_f32_16x16x32_bf16 v[32:35], v[160:163], v[66:69], 0
	ds_read_b128 v[160:163], v223 offset:13824
	s_nop 0
	s_waitcnt lgkmcnt(5)
	v_mfma_f32_16x16x32_bf16 v[138:141], v[164:167], v[70:73], v[32:35]
	ds_read_b128 v[164:167], v223 offset:13888
	s_nop 5
	s_nop 0
	s_nop 0
	s_nop 0
	s_waitcnt lgkmcnt(5)
	v_mfma_f32_16x16x32_bf16 v[32:35], v[168:171], v[66:69], 0
	ds_read_b128 v[168:171], v223 offset:16128
	s_nop 0
	s_waitcnt lgkmcnt(5)
	v_mfma_f32_16x16x32_bf16 v[142:145], v[240:243], v[70:73], v[32:35]
	s_nop 5
	s_nop 0
	s_nop 0
	s_nop 0
	s_waitcnt lgkmcnt(4)
	v_mfma_f32_16x16x32_bf16 v[32:35], v[244:247], v[66:69], 0
	s_nop 0
	s_waitcnt lgkmcnt(3)
	v_mfma_f32_16x16x32_bf16 v[146:149], v[248:251], v[70:73], v[32:35]
	s_nop 5
	s_nop 0
	s_nop 0
	s_nop 0
	s_waitcnt lgkmcnt(2)
	v_mfma_f32_16x16x32_bf16 v[32:35], v[160:163], v[66:69], 0
	s_nop 0
	s_waitcnt lgkmcnt(1)
	v_mfma_f32_16x16x32_bf16 v[150:153], v[164:167], v[70:73], v[32:35]
	s_nop 5
	s_nop 0
	ds_read_b128 v[36:39], v223 offset:16192
	s_nop 0
	s_waitcnt lgkmcnt(1)
	v_mfma_f32_16x16x32_bf16 v[32:35], v[168:171], v[66:69], 0
	s_nop 0
	s_waitcnt lgkmcnt(0)
	v_mfma_f32_16x16x32_bf16 v[154:157], v[36:39], v[70:73], v[32:35]
	s_cbranch_scc0 .LBB0_1173
	s_nop 4
	v_add_u32_e32 v32, s19, v220
	v_cvt_f32_i32_e32 v32, v32
	s_add_i32 s9, s9, 15
	s_cmp_gt_i32 s19, s9
	v_mul_f32_e32 v32, v188, v32
	v_exp_f32_e32 v182, v32
	s_cbranch_scc1 .LBB0_1170
	s_waitcnt lgkmcnt(0)
	ds_read_b128 v[32:35], v206
	ds_read_b128 v[36:39], v207
	v_add_u32_e32 v62, s19, v191
	v_add_u32_e32 v63, 16, v62
	ds_read_b128 v[40:43], v205
	ds_read_b128 v[240:243], v204
	v_or_b32_e32 v44, 2, v63
	s_nop 0
	s_waitcnt lgkmcnt(3)
	v_pk_mul_f32 v[34:35], v[182:183], v[34:35] op_sel_hi:[0,1]
	v_cmp_ne_u32_e32 vcc, v6, v44
	ds_read_b128 v[244:247], v208
	ds_read_b128 v[158:161], v209
	v_cndmask_b32_e32 v34, v237, v34, vcc
	v_cmp_gt_i32_e32 vcc, v6, v44
	v_or_b32_e32 v44, 3, v63
	s_nop 0
	s_waitcnt lgkmcnt(3)
	v_pk_mul_f32 v[42:43], v[64:65], v[42:43] op_sel_hi:[0,1]
	v_cmp_ne_u32_e64 s[6:7], v7, v44
	v_add_u32_e32 v183, 32, v62
	v_cndmask_b32_e32 v184, v34, v42, vcc
	v_cndmask_b32_e64 v35, v237, v35, s[6:7]
	v_cmp_gt_i32_e64 s[6:7], v7, v44
	v_or_b32_e32 v42, 2, v183
	v_cmp_ne_u32_e32 vcc, v10, v42
	v_cndmask_b32_e64 v185, v35, v43, s[6:7]
	s_nop 0
	s_waitcnt lgkmcnt(1)
	v_pk_mul_f32 v[34:35], v[182:183], v[246:247] op_sel_hi:[0,1]
	ds_read_b128 v[168:171], v210
	ds_read_b128 v[56:59], v211
	v_cndmask_b32_e32 v34, v237, v34, vcc
	v_cmp_gt_i32_e32 vcc, v10, v42
	v_or_b32_e32 v42, 3, v183
	v_cmp_ne_u32_e64 s[6:7], v11, v42
	v_add_u32_e32 v225, 48, v62
	v_pk_mul_f32 v[38:39], v[64:65], v[38:39] op_sel_hi:[0,1]
	v_cndmask_b32_e64 v35, v237, v35, s[6:7]
	v_cmp_gt_i32_e64 s[6:7], v11, v42
	v_or_b32_e32 v44, 2, v225
	v_cndmask_b32_e32 v38, v34, v38, vcc
	v_cndmask_b32_e64 v39, v35, v39, s[6:7]
	s_nop 0
	s_waitcnt lgkmcnt(1)
	v_pk_mul_f32 v[34:35], v[182:183], v[170:171] op_sel_hi:[0,1]
	v_cmp_ne_u32_e32 vcc, v14, v44
	ds_read_b128 v[164:167], v212
	ds_read_b128 v[50:53], v213
	v_cndmask_b32_e32 v34, v237, v34, vcc
	v_cmp_gt_i32_e32 vcc, v14, v44
	v_or_b32_e32 v44, 3, v225
	v_cmp_ne_u32_e64 s[6:7], v15, v44
	v_add_u32_e32 v250, 64, v62
	v_pk_mul_f32 v[42:43], v[64:65], v[160:161] op_sel_hi:[0,1]
	v_cndmask_b32_e64 v35, v237, v35, s[6:7]
	v_cmp_gt_i32_e64 s[6:7], v15, v44
	v_or_b32_e32 v44, 2, v250
	v_cndmask_b32_e32 v170, v34, v42, vcc
	v_cndmask_b32_e64 v171, v35, v43, s[6:7]
	s_nop 0
	s_waitcnt lgkmcnt(1)
	v_pk_mul_f32 v[34:35], v[182:183], v[166:167] op_sel_hi:[0,1]
	v_cmp_ne_u32_e32 vcc, v18, v44
	ds_read_b128 v[160:163], v214
	ds_read_b128 v[46:49], v215
	v_cndmask_b32_e32 v34, v237, v34, vcc
	v_cmp_gt_i32_e32 vcc, v18, v44
	v_or_b32_e32 v44, 3, v250
	v_cmp_ne_u32_e64 s[6:7], v19, v44
	v_add_u32_e32 v251, 0x50, v62
	v_pk_mul_f32 v[42:43], v[64:65], v[58:59] op_sel_hi:[0,1]
	v_cndmask_b32_e64 v35, v237, v35, s[6:7]
	v_cmp_gt_i32_e64 s[6:7], v19, v44
	v_or_b32_e32 v44, 2, v251
	v_cndmask_b32_e32 v166, v34, v42, vcc
	v_cndmask_b32_e64 v167, v35, v43, s[6:7]
	s_nop 0
	s_waitcnt lgkmcnt(1)
	v_pk_mul_f32 v[34:35], v[182:183], v[162:163] op_sel_hi:[0,1]
	v_cmp_ne_u32_e32 vcc, v22, v44
	v_pk_mul_f32 v[42:43], v[64:65], v[52:53] op_sel_hi:[0,1]
	v_add_u32_e32 v252, 0x60, v62
	v_cndmask_b32_e32 v34, v237, v34, vcc
	v_cmp_gt_i32_e32 vcc, v22, v44
	v_or_b32_e32 v44, 3, v251
	v_cmp_ne_u32_e64 s[6:7], v23, v44
	v_cndmask_b32_e32 v162, v34, v42, vcc
	v_or_b32_e32 v52, 2, v252
	v_cndmask_b32_e64 v35, v237, v35, s[6:7]
	v_cmp_gt_i32_e64 s[6:7], v23, v44
	v_cmp_ne_u32_e32 vcc, v26, v52
	s_nop 0
	s_waitcnt lgkmcnt(0)
	v_pk_mul_f32 v[48:49], v[64:65], v[48:49] op_sel_hi:[0,1]
	v_cndmask_b32_e64 v163, v35, v43, s[6:7]
	ds_read_b128 v[58:61], v216
	ds_read_b128 v[42:45], v217
	v_add_u32_e32 v253, 0x70, v62
	v_add_u32_e32 v226, 1, v62
	v_pk_mul_f32 v[32:33], v[182:183], v[32:33] op_sel_hi:[0,1]
	s_nop 0
	s_waitcnt lgkmcnt(1)
	v_pk_mul_f32 v[34:35], v[182:183], v[60:61] op_sel_hi:[0,1]
	v_cndmask_b32_e32 v34, v237, v34, vcc
	v_cmp_gt_i32_e32 vcc, v26, v52
	v_or_b32_e32 v52, 3, v252
	v_cmp_ne_u32_e64 s[6:7], v27, v52
	v_cndmask_b32_e32 v48, v34, v48, vcc
	v_add_u32_e32 v34, 0x12200, v202
	v_cndmask_b32_e64 v35, v237, v35, s[6:7]
	v_cmp_gt_i32_e64 s[6:7], v27, v52
	ds_read_b128 v[246:249], v34
	ds_read_b128 v[52:55], v218
	v_cndmask_b32_e64 v49, v35, v49, s[6:7]
	v_or_b32_e32 v60, 2, v253
	v_cmp_ne_u32_e32 vcc, v30, v60
	s_nop 0
	s_waitcnt lgkmcnt(2)
	v_pk_mul_f32 v[44:45], v[64:65], v[44:45] op_sel_hi:[0,1]
	s_nop 0
	s_waitcnt lgkmcnt(0)
	v_pk_mul_f32 v[34:35], v[182:183], v[54:55] op_sel_hi:[0,1]
	v_or_b32_e32 v54, 3, v253
	v_cmp_ne_u32_e64 s[6:7], v31, v54
	v_cndmask_b32_e32 v34, v237, v34, vcc
	v_cmp_gt_i32_e32 vcc, v30, v60
	v_cndmask_b32_e64 v35, v237, v35, s[6:7]
	v_cmp_gt_i32_e64 s[6:7], v31, v54
	v_or_b32_e32 v60, 2, v62
	v_cndmask_b32_e32 v44, v34, v44, vcc
	v_cndmask_b32_e64 v45, v35, v45, s[6:7]
	v_pk_mul_f32 v[34:35], v[182:183], v[248:249] op_sel_hi:[0,1]
	v_cmp_ne_u32_e32 vcc, v2, v60
	v_pk_mul_f32 v[54:55], v[64:65], v[242:243] op_sel_hi:[0,1]
	v_pk_mul_f32 v[40:41], v[64:65], v[40:41] op_sel_hi:[0,1]
	v_cndmask_b32_e32 v34, v237, v34, vcc
	v_cmp_gt_i32_e32 vcc, v2, v60
	v_or_b32_e32 v60, 3, v62
	v_cmp_ne_u32_e64 s[6:7], v3, v60
	v_cndmask_b32_e32 v34, v34, v54, vcc
	v_cmp_ne_u32_e32 vcc, v1, v226
	v_cndmask_b32_e64 v35, v237, v35, s[6:7]
	v_cmp_gt_i32_e64 s[6:7], v3, v60
	v_pk_mul_f32 v[60:61], v[182:183], v[246:247] op_sel_hi:[0,1]
	v_cndmask_b32_e32 v61, v237, v61, vcc
	v_cndmask_b32_e64 v35, v35, v55, s[6:7]
	v_cmp_ne_u32_e64 s[6:7], v0, v62
	v_pk_mul_f32 v[54:55], v[64:65], v[240:241] op_sel_hi:[0,1]
	v_cmp_gt_i32_e32 vcc, v1, v226
	v_cndmask_b32_e64 v60, v237, v60, s[6:7]
	v_cmp_gt_i32_e64 s[6:7], v0, v62
	v_cndmask_b32_e32 v227, v61, v55, vcc
	v_cmp_ne_u32_e32 vcc, v4, v63
	v_cndmask_b32_e64 v226, v60, v54, s[6:7]
	v_add_u32_e32 v54, 17, v62
	v_cmp_ne_u32_e64 s[6:7], v5, v54
	v_cndmask_b32_e32 v32, v237, v32, vcc
	v_cmp_gt_i32_e32 vcc, v4, v63
	v_cndmask_b32_e64 v33, v237, v33, s[6:7]
	v_cmp_gt_i32_e64 s[6:7], v5, v54
	v_add_u32_e32 v54, 33, v62
	v_cndmask_b32_e32 v32, v32, v40, vcc
	v_cndmask_b32_e64 v33, v33, v41, s[6:7]
	v_pk_mul_f32 v[40:41], v[182:183], v[244:245] op_sel_hi:[0,1]
	v_cmp_ne_u32_e32 vcc, v8, v183
	v_cmp_ne_u32_e64 s[6:7], v9, v54
	v_pk_mul_f32 v[36:37], v[64:65], v[36:37] op_sel_hi:[0,1]
	v_cndmask_b32_e32 v40, v237, v40, vcc
	v_cmp_gt_i32_e32 vcc, v8, v183
	v_cndmask_b32_e64 v41, v237, v41, s[6:7]
	v_cmp_gt_i32_e64 s[6:7], v9, v54
	v_add_u32_e32 v60, 49, v62
	v_cndmask_b32_e32 v36, v40, v36, vcc
	v_cndmask_b32_e64 v37, v41, v37, s[6:7]
	v_pk_mul_f32 v[54:55], v[182:183], v[168:169] op_sel_hi:[0,1]
	v_cmp_ne_u32_e32 vcc, v12, v225
	v_cmp_ne_u32_e64 s[6:7], v13, v60
	v_pk_mul_f32 v[40:41], v[64:65], v[158:159] op_sel_hi:[0,1]
	v_cndmask_b32_e32 v54, v237, v54, vcc
	v_cmp_gt_i32_e32 vcc, v12, v225
	v_cndmask_b32_e64 v55, v237, v55, s[6:7]
	v_cmp_gt_i32_e64 s[6:7], v13, v60
	v_cndmask_b32_e32 v40, v54, v40, vcc
	v_cmp_ne_u32_e32 vcc, v16, v250
	v_cndmask_b32_e64 v41, v55, v41, s[6:7]
	v_pk_mul_f32 v[54:55], v[64:65], v[56:57] op_sel_hi:[0,1]
	v_pk_mul_f32 v[56:57], v[182:183], v[164:165] op_sel_hi:[0,1]
	v_add_u32_e32 v60, 0x41, v62
	v_cndmask_b32_e32 v56, v237, v56, vcc
	v_cmp_gt_i32_e32 vcc, v16, v250
	v_cmp_ne_u32_e64 s[6:7], v17, v60
	v_pk_mul_f32 v[50:51], v[64:65], v[50:51] op_sel_hi:[0,1]
	v_cndmask_b32_e32 v158, v56, v54, vcc
	v_cndmask_b32_e64 v57, v237, v57, s[6:7]
	v_cmp_gt_i32_e64 s[6:7], v17, v60
	v_add_u32_e32 v56, 0x51, v62
	v_cmp_ne_u32_e32 vcc, v20, v251
	v_cndmask_b32_e64 v159, v57, v55, s[6:7]
	v_pk_mul_f32 v[54:55], v[182:183], v[160:161] op_sel_hi:[0,1]
	v_cmp_ne_u32_e64 s[6:7], v21, v56
	v_cndmask_b32_e32 v54, v237, v54, vcc
	v_cmp_gt_i32_e32 vcc, v20, v251
	v_cndmask_b32_e64 v55, v237, v55, s[6:7]
	v_cmp_gt_i32_e64 s[6:7], v21, v56
	v_cndmask_b32_e32 v160, v54, v50, vcc
	v_cmp_ne_u32_e32 vcc, v24, v252
	v_cndmask_b32_e64 v161, v55, v51, s[6:7]
	v_pk_mul_f32 v[50:51], v[182:183], v[58:59] op_sel_hi:[0,1]
	v_add_u32_e32 v54, 0x61, v62
	v_pk_mul_f32 v[46:47], v[64:65], v[46:47] op_sel_hi:[0,1]
	v_cndmask_b32_e32 v50, v237, v50, vcc
	v_cmp_gt_i32_e32 vcc, v24, v252
	v_cmp_ne_u32_e64 s[6:7], v25, v54
	v_pk_mul_f32 v[42:43], v[64:65], v[42:43] op_sel_hi:[0,1]
	v_cndmask_b32_e32 v56, v50, v46, vcc
	v_cndmask_b32_e64 v51, v237, v51, s[6:7]
	v_cmp_gt_i32_e64 s[6:7], v25, v54
	v_add_u32_e32 v50, 0x71, v62
	v_cmp_ne_u32_e32 vcc, v28, v253
	v_cndmask_b32_e64 v57, v51, v47, s[6:7]
	v_pk_mul_f32 v[46:47], v[182:183], v[52:53] op_sel_hi:[0,1]
	v_cmp_ne_u32_e64 s[6:7], v29, v50
	v_cndmask_b32_e32 v46, v237, v46, vcc
	v_cmp_gt_i32_e32 vcc, v28, v253
	v_cndmask_b32_e64 v47, v237, v47, s[6:7]
	v_cmp_gt_i32_e64 s[6:7], v29, v50
	v_cndmask_b32_e32 v52, v46, v42, vcc
	v_pk_mul_f32 v[34:35], v[128:129], v[34:35]
	v_cndmask_b32_e64 v53, v47, v43, s[6:7]
	v_pk_mul_f32 v[62:63], v[156:157], v[44:45]
	v_pk_mul_f32 v[58:59], v[152:153], v[48:49]
	v_pk_mul_f32 v[54:55], v[148:149], v[162:163]
	v_pk_mul_f32 v[50:51], v[144:145], v[166:167]
	v_pk_mul_f32 v[46:47], v[140:141], v[170:171]
	v_pk_mul_f32 v[42:43], v[136:137], v[38:39]
	v_pk_mul_f32 v[38:39], v[132:133], v[184:185]
	v_pk_mul_f32 v[60:61], v[154:155], v[52:53]
	v_pk_mul_f32 v[56:57], v[150:151], v[56:57]
	v_pk_mul_f32 v[52:53], v[146:147], v[160:161]
	v_pk_mul_f32 v[48:49], v[142:143], v[158:159]
	v_pk_mul_f32 v[44:45], v[138:139], v[40:41]
	v_pk_mul_f32 v[40:41], v[134:135], v[36:37]
	v_pk_mul_f32 v[36:37], v[130:131], v[32:33]
	v_pk_mul_f32 v[32:33], v[126:127], v[226:227]
	s_mov_b64 s[6:7], 0
.LBB0_1170:
	s_andn2_b64 vcc, exec, s[6:7]
	s_cbranch_vccnz .LBB0_1172
	s_waitcnt lgkmcnt(0)
	v_add_u32_e32 v60, 0x12200, v202
	ds_read_b128 v[160:163], v60
	ds_read_b128 v[164:167], v60 offset:64
	ds_read_b128 v[168:171], v60 offset:128
	ds_read_b128 v[240:243], v60 offset:192
	ds_read_b128 v[244:247], v60 offset:256
	ds_read_b128 v[248:251], v60 offset:320
	ds_read_b128 v[56:59], v60 offset:384
	ds_read_b128 v[60:63], v60 offset:448
	s_nop 0
	s_waitcnt lgkmcnt(7)
	v_pk_mul_f32 v[34:35], v[182:183], v[162:163] op_sel_hi:[0,1]
	s_nop 0
	s_waitcnt lgkmcnt(6)
	v_pk_mul_f32 v[38:39], v[182:183], v[166:167] op_sel_hi:[0,1]
	s_nop 0
	s_waitcnt lgkmcnt(5)
	v_pk_mul_f32 v[42:43], v[182:183], v[170:171] op_sel_hi:[0,1]
	s_nop 0
	s_waitcnt lgkmcnt(4)
	v_pk_mul_f32 v[46:47], v[182:183], v[242:243] op_sel_hi:[0,1]
	s_nop 0
	s_waitcnt lgkmcnt(3)
	v_pk_mul_f32 v[50:51], v[182:183], v[246:247] op_sel_hi:[0,1]
	s_nop 0
	s_waitcnt lgkmcnt(2)
	v_pk_mul_f32 v[54:55], v[182:183], v[250:251] op_sel_hi:[0,1]
	s_nop 0
	s_waitcnt lgkmcnt(1)
	v_pk_mul_f32 v[58:59], v[182:183], v[58:59] op_sel_hi:[0,1]
	s_nop 0
	s_waitcnt lgkmcnt(0)
	v_pk_mul_f32 v[62:63], v[182:183], v[62:63] op_sel_hi:[0,1]
	v_pk_mul_f32 v[32:33], v[182:183], v[160:161] op_sel_hi:[0,1]
	v_pk_mul_f32 v[36:37], v[182:183], v[164:165] op_sel_hi:[0,1]
	v_pk_mul_f32 v[40:41], v[182:183], v[168:169] op_sel_hi:[0,1]
	v_pk_mul_f32 v[44:45], v[182:183], v[240:241] op_sel_hi:[0,1]
	v_pk_mul_f32 v[48:49], v[182:183], v[244:245] op_sel_hi:[0,1]
	v_pk_mul_f32 v[52:53], v[182:183], v[248:249] op_sel_hi:[0,1]
	v_pk_mul_f32 v[56:57], v[182:183], v[56:57] op_sel_hi:[0,1]
	v_pk_mul_f32 v[60:61], v[182:183], v[60:61] op_sel_hi:[0,1]
	v_pk_mul_f32 v[60:61], v[154:155], v[60:61]
	v_pk_mul_f32 v[56:57], v[150:151], v[56:57]
	v_pk_mul_f32 v[52:53], v[146:147], v[52:53]
	v_pk_mul_f32 v[48:49], v[142:143], v[48:49]
	v_pk_mul_f32 v[44:45], v[138:139], v[44:45]
	v_pk_mul_f32 v[40:41], v[134:135], v[40:41]
	v_pk_mul_f32 v[36:37], v[130:131], v[36:37]
	v_pk_mul_f32 v[32:33], v[126:127], v[32:33]
	v_pk_mul_f32 v[62:63], v[156:157], v[62:63]
	v_pk_mul_f32 v[58:59], v[152:153], v[58:59]
	v_pk_mul_f32 v[54:55], v[148:149], v[54:55]
	v_pk_mul_f32 v[50:51], v[144:145], v[50:51]
	v_pk_mul_f32 v[46:47], v[140:141], v[46:47]
	v_pk_mul_f32 v[42:43], v[136:137], v[42:43]
	v_pk_mul_f32 v[38:39], v[132:133], v[38:39]
	v_pk_mul_f32 v[34:35], v[128:129], v[34:35]

.LBB0_1173:
	s_andn2_b64 vcc, exec, s[6:7]
	s_cbranch_vccnz .LBB0_1175
	s_waitcnt lgkmcnt(0)
	v_add_u32_e32 v60, 0x12000, v202
	ds_read_b128 v[160:163], v60
	ds_read_b128 v[164:167], v60 offset:64
	ds_read_b128 v[168:171], v60 offset:128
	ds_read_b128 v[240:243], v60 offset:192
	ds_read_b128 v[244:247], v60 offset:256
	ds_read_b128 v[248:251], v60 offset:320
	s_nop 1
	s_nop 0
	s_nop 0
	s_nop 0
	s_nop 0
	s_nop 0
	s_nop 0
	ds_read_b128 v[56:59], v60 offset:384
	ds_read_b128 v[60:63], v60 offset:448
	s_nop 0
	s_waitcnt lgkmcnt(7)
	v_pk_mul_f32 v[34:35], v[64:65], v[162:163] op_sel_hi:[0,1]
	s_nop 0
	s_waitcnt lgkmcnt(6)
	v_pk_mul_f32 v[38:39], v[64:65], v[166:167] op_sel_hi:[0,1]
	s_nop 0
	s_waitcnt lgkmcnt(5)
	v_pk_mul_f32 v[42:43], v[64:65], v[170:171] op_sel_hi:[0,1]
	s_nop 0
	s_waitcnt lgkmcnt(4)
	v_pk_mul_f32 v[46:47], v[64:65], v[242:243] op_sel_hi:[0,1]
	s_nop 0
	s_waitcnt lgkmcnt(3)
	v_pk_mul_f32 v[50:51], v[64:65], v[246:247] op_sel_hi:[0,1]
	s_nop 0
	s_waitcnt lgkmcnt(2)
	v_pk_mul_f32 v[54:55], v[64:65], v[250:251] op_sel_hi:[0,1]
	s_nop 0
	s_waitcnt lgkmcnt(1)
	v_pk_mul_f32 v[58:59], v[64:65], v[58:59] op_sel_hi:[0,1]
	s_nop 0
	s_waitcnt lgkmcnt(0)
	v_pk_mul_f32 v[62:63], v[64:65], v[62:63] op_sel_hi:[0,1]
	v_pk_mul_f32 v[32:33], v[64:65], v[160:161] op_sel_hi:[0,1]
	v_pk_mul_f32 v[36:37], v[64:65], v[164:165] op_sel_hi:[0,1]
	v_pk_mul_f32 v[40:41], v[64:65], v[168:169] op_sel_hi:[0,1]
	v_pk_mul_f32 v[44:45], v[64:65], v[240:241] op_sel_hi:[0,1]
	v_pk_mul_f32 v[48:49], v[64:65], v[244:245] op_sel_hi:[0,1]
	v_pk_mul_f32 v[52:53], v[64:65], v[248:249] op_sel_hi:[0,1]
	v_pk_mul_f32 v[56:57], v[64:65], v[56:57] op_sel_hi:[0,1]
	v_pk_mul_f32 v[60:61], v[64:65], v[60:61] op_sel_hi:[0,1]
	v_pk_mul_f32 v[60:61], v[154:155], v[60:61]
	v_pk_mul_f32 v[56:57], v[150:151], v[56:57]
	v_pk_mul_f32 v[52:53], v[146:147], v[52:53]
	v_pk_mul_f32 v[48:49], v[142:143], v[48:49]
	v_pk_mul_f32 v[44:45], v[138:139], v[44:45]
	v_pk_mul_f32 v[40:41], v[134:135], v[40:41]
	v_pk_mul_f32 v[36:37], v[130:131], v[36:37]
	v_pk_mul_f32 v[32:33], v[126:127], v[32:33]
	v_pk_mul_f32 v[62:63], v[156:157], v[62:63]
	v_pk_mul_f32 v[58:59], v[152:153], v[58:59]
	v_pk_mul_f32 v[54:55], v[148:149], v[54:55]
	v_pk_mul_f32 v[50:51], v[144:145], v[50:51]
	v_pk_mul_f32 v[46:47], v[140:141], v[46:47]
	v_pk_mul_f32 v[42:43], v[136:137], v[42:43]
	v_pk_mul_f32 v[38:39], v[132:133], v[38:39]
	v_pk_mul_f32 v[34:35], v[128:129], v[34:35]
.LBB0_1175:
	s_waitcnt lgkmcnt(0)
	ds_read_b64_tr_b16 v[150:151], v203 offset:20736
	ds_read_b64_tr_b16 v[148:149], v203 offset:18432
	ds_read_b64_tr_b16 v[152:153], v203 offset:18464
	ds_read_b64_tr_b16 v[154:155], v203 offset:20768
	ds_read_b64_tr_b16 v[156:157], v203 offset:18496
	ds_read_b64_tr_b16 v[158:159], v203 offset:20800
	ds_read_b64_tr_b16 v[160:161], v203 offset:18528
	ds_read_b64_tr_b16 v[162:163], v203 offset:20832
	v_cvt_pk_bf16_f32 v128, v36, v37
	v_cvt_pk_bf16_f32 v40, v40, v41
	v_cvt_pk_bf16_f32 v41, v42, v43
	v_cvt_pk_bf16_f32 v42, v44, v45
	v_cvt_pk_bf16_f32 v43, v46, v47
	v_cvt_pk_bf16_f32 v36, v48, v49
	v_cvt_pk_bf16_f32 v37, v50, v51
	s_nop 0
	s_nop 0
	s_nop 0
	s_nop 0
	v_cvt_pk_bf16_f32 v126, v32, v33
	v_cvt_pk_bf16_f32 v127, v34, v35
	v_cvt_pk_bf16_f32 v129, v38, v39
	v_cvt_pk_bf16_f32 v38, v52, v53
	v_cvt_pk_bf16_f32 v39, v54, v55
	v_cvt_pk_bf16_f32 v32, v56, v57
	v_cvt_pk_bf16_f32 v33, v58, v59
	v_cvt_pk_bf16_f32 v34, v60, v61
	v_cvt_pk_bf16_f32 v35, v62, v63
	s_nop 0
	s_nop 0
	s_nop 0
	s_nop 0
	ds_read_b64_tr_b16 v[164:165], v203 offset:23040
	ds_read_b64_tr_b16 v[166:167], v203 offset:25344
	s_nop 0
	s_waitcnt lgkmcnt(8)
	v_mfma_f32_16x16x32_bf16 v[44:47], v[148:151], v[126:129], v[118:121]
	s_nop 0
	s_waitcnt lgkmcnt(0)
	v_mfma_f32_16x16x32_bf16 v[44:47], v[164:167], v[40:43], v[44:47]
	ds_read_b64_tr_b16 v[148:149], v203 offset:23072
	ds_read_b64_tr_b16 v[150:151], v203 offset:25376
	v_mfma_f32_16x16x32_bf16 v[48:51], v[152:155], v[126:129], v[122:125]
	ds_read_b64_tr_b16 v[152:153], v203 offset:23104
	ds_read_b64_tr_b16 v[154:155], v203 offset:25408
	s_nop 0
	s_waitcnt lgkmcnt(2)
	v_mfma_f32_16x16x32_bf16 v[48:51], v[148:151], v[40:43], v[48:51]
	s_nop 0
	s_nop 0
	ds_read_b64_tr_b16 v[148:149], v203 offset:27648
	ds_read_b64_tr_b16 v[150:151], v203 offset:29952
	v_mfma_f32_16x16x32_bf16 v[52:55], v[156:159], v[126:129], v[114:117]
	ds_read_b64_tr_b16 v[156:157], v203 offset:27680
	ds_read_b64_tr_b16 v[158:159], v203 offset:29984
	s_nop 0
	s_waitcnt lgkmcnt(4)
	v_mfma_f32_16x16x32_bf16 v[52:55], v[152:155], v[40:43], v[52:55]
	ds_read_b64_tr_b16 v[152:153], v203 offset:27712
	ds_read_b64_tr_b16 v[154:155], v203 offset:30016
	ds_read_b64_tr_b16 v[60:61], v203 offset:23136
	ds_read_b64_tr_b16 v[62:63], v203 offset:25440
	v_mfma_f32_16x16x32_bf16 v[56:59], v[160:163], v[126:129], v[110:113]
	ds_read_b64_tr_b16 v[160:161], v203 offset:32256
	ds_read_b64_tr_b16 v[162:163], v203 offset:34560
	s_nop 0
	s_waitcnt lgkmcnt(2)
	v_mfma_f32_16x16x32_bf16 v[40:43], v[60:63], v[40:43], v[56:59]
	s_nop 5
	s_nop 0
	s_nop 0
	s_nop 0
	v_mfma_f32_16x16x32_bf16 v[44:47], v[148:151], v[36:39], v[44:47]
	s_nop 0
	s_nop 0
	ds_read_b64_tr_b16 v[148:149], v203 offset:32288
	ds_read_b64_tr_b16 v[150:151], v203 offset:34592
	s_nop 0
	v_mfma_f32_16x16x32_bf16 v[48:51], v[156:159], v[36:39], v[48:51]
	s_nop 0
	s_nop 0
	ds_read_b64_tr_b16 v[156:157], v203 offset:32320
	ds_read_b64_tr_b16 v[158:159], v203 offset:34624
	s_nop 0
	v_mfma_f32_16x16x32_bf16 v[52:55], v[152:155], v[36:39], v[52:55]
	ds_read_b64_tr_b16 v[56:57], v203 offset:27744
	ds_read_b64_tr_b16 v[58:59], v203 offset:30048
	s_nop 0
	s_waitcnt lgkmcnt(0)
	v_mfma_f32_16x16x32_bf16 v[36:39], v[56:59], v[36:39], v[40:43]
	s_nop 2
	s_nop 0
	s_nop 0
	s_nop 0
	v_mfma_f32_16x16x32_bf16 v[126:129], v[160:163], v[32:35], v[44:47]
	s_nop 0
	s_nop 0
	s_nop 0
	v_mfma_f32_16x16x32_bf16 v[130:133], v[148:151], v[32:35], v[48:51]
	s_nop 0
	s_nop 0
	s_nop 0
	v_mfma_f32_16x16x32_bf16 v[134:137], v[156:159], v[32:35], v[52:55]
	ds_read_b64_tr_b16 v[40:41], v203 offset:32352
	ds_read_b64_tr_b16 v[42:43], v203 offset:34656
	s_nop 0
	s_waitcnt lgkmcnt(0)
	v_mfma_f32_16x16x32_bf16 v[138:141], v[40:43], v[32:35], v[36:39]

.LBB0_1186:
	ds_read_b128 v[32:35], v223 offset:41472
	ds_read_b128 v[36:39], v223 offset:41536
	s_mov_b64 s[6:7], -1
	s_and_b64 vcc, exec, s[10:11]
	s_cbranch_vccz .LBB0_1188
	s_waitcnt lgkmcnt(0)
	ds_read_b128 v[148:151], v223 offset:36864
	ds_read_b128 v[152:155], v223 offset:36928
	ds_read_b128 v[156:159], v223 offset:39168
	ds_read_b128 v[160:163], v223 offset:39232
	ds_read_b128 v[164:167], v223 offset:43776
	ds_read_b128 v[168:171], v223 offset:43840
	ds_read_b64_tr_b16 v[242:243], v203 offset:57600
	ds_read_b64_tr_b16 v[240:241], v203 offset:55296
	s_mov_b64 s[6:7], 0
	s_nop 0
	s_waitcnt lgkmcnt(7)
	v_mfma_f32_16x16x32_bf16 v[40:43], v[148:151], v[66:69], 0
	ds_read_b64_tr_b16 v[148:149], v203 offset:55328
	s_nop 0
	s_waitcnt lgkmcnt(7)
	v_mfma_f32_16x16x32_bf16 v[40:43], v[152:155], v[70:73], v[40:43]
	s_nop 0
	s_nop 0
	s_nop 0
	s_nop 0
	ds_read_b64_tr_b16 v[150:151], v203 offset:57632
	s_nop 0
	s_waitcnt lgkmcnt(7)
	v_mfma_f32_16x16x32_bf16 v[44:47], v[156:159], v[66:69], 0
	ds_read_b64_tr_b16 v[152:153], v203 offset:55360
	s_nop 1
	v_mul_f32_e64 v40, v178, v40
	v_mul_f32_e64 v41, v179, v41
	v_pk_mul_f32 v[42:43], v[178:179], v[42:43]
	v_cvt_pk_bf16_f32 v40, v40, v41
	s_nop 0
	s_waitcnt lgkmcnt(7)
	v_mfma_f32_16x16x32_bf16 v[44:47], v[160:163], v[70:73], v[44:47]
	ds_read_b64_tr_b16 v[154:155], v203 offset:57664
	v_cvt_pk_bf16_f32 v41, v42, v43
	v_mfma_f32_16x16x32_bf16 v[48:51], v[32:35], v[66:69], 0
	s_nop 0
	s_waitcnt lgkmcnt(7)
	v_mfma_f32_16x16x32_bf16 v[52:55], v[164:167], v[66:69], 0
	ds_read_b64_tr_b16 v[156:157], v203 offset:55392
	s_nop 3
	v_mul_f32_e64 v44, v178, v44
	v_mul_f32_e64 v45, v179, v45
	v_pk_mul_f32 v[46:47], v[178:179], v[46:47]
	v_cvt_pk_bf16_f32 v42, v44, v45
	v_mfma_f32_16x16x32_bf16 v[48:51], v[36:39], v[70:73], v[48:51]
	v_cvt_pk_bf16_f32 v43, v46, v47
	s_nop 0
	s_waitcnt lgkmcnt(7)
	v_mfma_f32_16x16x32_bf16 v[52:55], v[168:171], v[70:73], v[52:55]
	ds_read_b64_tr_b16 v[158:159], v203 offset:57696
	s_nop 4
	v_mul_f32_e64 v48, v178, v48
	v_mul_f32_e64 v49, v179, v49
	v_pk_mul_f32 v[50:51], v[178:179], v[50:51]
	v_pk_mul_f32 v[52:53], v[178:179], v[52:53]
	v_pk_mul_f32 v[54:55], v[178:179], v[54:55]
	v_cvt_pk_bf16_f32 v44, v48, v49
	v_cvt_pk_bf16_f32 v45, v50, v51
	v_cvt_pk_bf16_f32 v46, v52, v53
	v_cvt_pk_bf16_f32 v47, v54, v55
	s_nop 0
	s_nop 0
	s_nop 0
	s_nop 0
	s_nop 0
	s_nop 0
	s_nop 0
	s_nop 0
	s_nop 0
	s_waitcnt lgkmcnt(6)
	v_mfma_f32_16x16x32_bf16 v[48:51], v[240:243], v[40:43], v[126:129]
	ds_read_b64_tr_b16 v[160:161], v203 offset:59936
	ds_read_b64_tr_b16 v[162:163], v203 offset:62240
	s_nop 0
	s_waitcnt lgkmcnt(6)
	v_mfma_f32_16x16x32_bf16 v[52:55], v[148:151], v[40:43], v[130:133]
	ds_read_b64_tr_b16 v[148:149], v203 offset:59968
	ds_read_b64_tr_b16 v[150:151], v203 offset:62272
	s_nop 0
	s_waitcnt lgkmcnt(6)
	v_mfma_f32_16x16x32_bf16 v[56:59], v[152:155], v[40:43], v[134:137]
	s_nop 0
	s_waitcnt lgkmcnt(4)
	v_mfma_f32_16x16x32_bf16 v[40:43], v[156:159], v[40:43], v[138:141]
	ds_read_b64_tr_b16 v[60:61], v203 offset:59904
	ds_read_b64_tr_b16 v[62:63], v203 offset:62208
	s_nop 0
	s_waitcnt lgkmcnt(0)
	v_mfma_f32_16x16x32_bf16 v[118:121], v[60:63], v[44:47], v[48:51]
	s_nop 2
	s_nop 0
	s_nop 0
	s_nop 0
	v_mfma_f32_16x16x32_bf16 v[122:125], v[160:163], v[44:47], v[52:55]
	s_nop 0
	s_nop 0
	s_nop 0
	v_mfma_f32_16x16x32_bf16 v[114:117], v[148:151], v[44:47], v[56:59]
	ds_read_b64_tr_b16 v[48:49], v203 offset:60000
	ds_read_b64_tr_b16 v[50:51], v203 offset:62304
	s_nop 0
	s_waitcnt lgkmcnt(0)
	v_mfma_f32_16x16x32_bf16 v[110:113], v[48:51], v[44:47], v[40:43]
.LBB0_1188:
	s_andn2_b64 vcc, exec, s[6:7]
	s_cbranch_vccnz .LBB0_1154
	s_waitcnt lgkmcnt(0)
	ds_read_b128 v[160:163], v223 offset:36864
	ds_read_b128 v[164:167], v223 offset:36928
	ds_read_b128 v[168:171], v223 offset:39168
	ds_read_b128 v[240:243], v223 offset:43776
	ds_read_b128 v[244:247], v223 offset:43840
	ds_read_b128 v[248:251], v223 offset:46080
	s_nop 0
	v_add_u32_e32 v40, 0xffffff80, v224
	v_cvt_f32_i32_e32 v40, v40
	s_nop 0
	v_mfma_f32_16x16x32_bf16 v[32:35], v[32:35], v[66:69], 0
	s_add_i32 s10, s19, 0xff
	v_readfirstlane_b32 s9, v186
	v_mul_f32_e32 v48, v187, v40
	s_nop 0
	s_nop 0
	s_nop 0
	v_mfma_f32_16x16x32_bf16 v[118:121], v[36:39], v[70:73], v[32:35]
	v_exp_f32_e32 v64, v48
	s_mov_b64 s[6:7], -1
	s_cmp_ge_i32 s10, s9
	s_nop 0
	s_waitcnt lgkmcnt(5)
	v_mfma_f32_16x16x32_bf16 v[40:43], v[160:163], v[66:69], 0
	ds_read_b128 v[160:163], v223 offset:46144
	s_nop 0
	s_waitcnt lgkmcnt(5)
	v_mfma_f32_16x16x32_bf16 v[110:113], v[164:167], v[70:73], v[40:43]
	ds_read_b128 v[164:167], v223 offset:48384
	s_nop 5
	s_nop 0
	ds_read_b128 v[44:47], v223 offset:39232
	s_nop 0
	s_nop 0
	s_nop 0
	s_waitcnt lgkmcnt(5)
	v_mfma_f32_16x16x32_bf16 v[32:35], v[240:243], v[66:69], 0
	ds_read_b128 v[240:243], v223 offset:48448
	s_nop 0
	s_waitcnt lgkmcnt(5)
	v_mfma_f32_16x16x32_bf16 v[122:125], v[244:247], v[70:73], v[32:35]
	ds_read_b128 v[244:247], v223 offset:50688
	s_nop 5
	s_nop 0
	s_nop 0
	s_nop 0
	s_waitcnt lgkmcnt(5)
	v_mfma_f32_16x16x32_bf16 v[32:35], v[248:251], v[66:69], 0
	ds_read_b128 v[248:251], v223 offset:50752
	s_nop 0
	s_waitcnt lgkmcnt(5)
	v_mfma_f32_16x16x32_bf16 v[142:145], v[160:163], v[70:73], v[32:35]
	ds_read_b128 v[160:163], v223 offset:52992
	s_nop 5
	s_nop 0
	s_nop 0
	s_nop 0
	s_waitcnt lgkmcnt(5)
	v_mfma_f32_16x16x32_bf16 v[32:35], v[164:167], v[66:69], 0
	s_nop 0
	s_waitcnt lgkmcnt(3)
	v_mfma_f32_16x16x32_bf16 v[146:149], v[240:243], v[70:73], v[32:35]
	s_nop 5
	s_nop 0
	s_nop 0
	s_nop 0
	s_waitcnt lgkmcnt(2)
	v_mfma_f32_16x16x32_bf16 v[32:35], v[244:247], v[66:69], 0
	s_nop 0
	s_waitcnt lgkmcnt(1)
	v_mfma_f32_16x16x32_bf16 v[150:153], v[248:251], v[70:73], v[32:35]
	s_nop 5
	s_nop 0
	ds_read_b128 v[36:39], v223 offset:53056
	v_mfma_f32_16x16x32_bf16 v[40:43], v[168:171], v[66:69], 0
	s_nop 0
	s_waitcnt lgkmcnt(1)
	v_mfma_f32_16x16x32_bf16 v[32:35], v[160:163], v[66:69], 0
	v_mfma_f32_16x16x32_bf16 v[114:117], v[44:47], v[70:73], v[40:43]
	s_nop 0
	s_waitcnt lgkmcnt(0)
	v_mfma_f32_16x16x32_bf16 v[154:157], v[36:39], v[70:73], v[32:35]
	s_cbranch_scc0 .LBB0_1195
	s_nop 3
	v_add_u32_e32 v32, s19, v220
	v_add_u32_e32 v32, 0x80, v32
	v_cvt_f32_i32_e32 v32, v32
	s_add_i32 s10, s19, 0x71
	s_cmp_gt_i32 s10, s9
	v_add_u32_e32 v171, 0x12200, v202
	v_mul_f32_e32 v32, v188, v32
	v_exp_f32_e32 v170, v32
	s_cbranch_scc1 .LBB0_1192
	s_waitcnt lgkmcnt(0)
	ds_read_b128 v[32:35], v171
	ds_read_b128 v[36:39], v218
	ds_read_b128 v[240:243], v204
	ds_read_b128 v[166:169], v205
	v_add_u32_e32 v184, s19, v191
	v_add_u32_e32 v185, 0x80, v184
	v_or_b32_e32 v42, 2, v185
	s_nop 0
	s_waitcnt lgkmcnt(3)
	v_pk_mul_f32 v[34:35], v[170:171], v[34:35] op_sel_hi:[0,1]
	v_cmp_ne_u32_e32 vcc, v2, v42
	s_nop 0
	s_waitcnt lgkmcnt(1)
	v_pk_mul_f32 v[40:41], v[64:65], v[242:243] op_sel_hi:[0,1]
	ds_read_b128 v[242:245], v206
	ds_read_b128 v[60:63], v207
	v_cndmask_b32_e32 v34, v237, v34, vcc
	v_cmp_gt_i32_e32 vcc, v2, v42
	v_or_b32_e32 v42, 3, v185
	v_cmp_ne_u32_e64 s[6:7], v3, v42
	v_add_u32_e32 v225, 0x90, v184
	v_or_b32_e32 v44, 2, v225
	v_cndmask_b32_e64 v35, v237, v35, s[6:7]
	v_cmp_gt_i32_e64 s[6:7], v3, v42
	v_cndmask_b32_e32 v34, v34, v40, vcc
	v_cmp_ne_u32_e32 vcc, v6, v44
	v_cndmask_b32_e64 v35, v35, v41, s[6:7]
	s_nop 0
	s_waitcnt lgkmcnt(1)
	v_pk_mul_f32 v[40:41], v[170:171], v[244:245] op_sel_hi:[0,1]
	ds_read_b128 v[244:247], v208
	ds_read_b128 v[54:57], v209
	v_cndmask_b32_e32 v40, v237, v40, vcc
	v_cmp_gt_i32_e32 vcc, v6, v44
	v_or_b32_e32 v44, 3, v225
	v_cmp_ne_u32_e64 s[6:7], v7, v44
	v_add_u32_e32 v226, 0xa0, v184
	v_pk_mul_f32 v[42:43], v[64:65], v[168:169] op_sel_hi:[0,1]
	v_cndmask_b32_e64 v41, v237, v41, s[6:7]
	v_cmp_gt_i32_e64 s[6:7], v7, v44
	v_or_b32_e32 v44, 2, v226
	v_cndmask_b32_e32 v168, v40, v42, vcc
	v_cndmask_b32_e64 v169, v41, v43, s[6:7]
	s_nop 0
	s_waitcnt lgkmcnt(1)
	v_pk_mul_f32 v[40:41], v[170:171], v[246:247] op_sel_hi:[0,1]
	v_cmp_ne_u32_e32 vcc, v10, v44
	ds_read_b128 v[162:165], v210
	ds_read_b128 v[48:51], v211
	v_cndmask_b32_e32 v40, v237, v40, vcc
	v_cmp_gt_i32_e32 vcc, v10, v44
	v_or_b32_e32 v44, 3, v226
	v_pk_mul_f32 v[42:43], v[64:65], v[62:63] op_sel_hi:[0,1]
	v_cmp_ne_u32_e64 s[6:7], v11, v44
	v_add_u32_e32 v62, 0xb0, v184
	v_cndmask_b32_e32 v182, v40, v42, vcc
	v_cndmask_b32_e64 v41, v237, v41, s[6:7]
	v_cmp_gt_i32_e64 s[6:7], v11, v44
	v_or_b32_e32 v44, 2, v62
	v_cmp_ne_u32_e32 vcc, v14, v44
	v_cndmask_b32_e64 v183, v41, v43, s[6:7]
	s_nop 0
	s_waitcnt lgkmcnt(1)
	v_pk_mul_f32 v[40:41], v[170:171], v[164:165] op_sel_hi:[0,1]
	v_cndmask_b32_e32 v40, v237, v40, vcc
	v_cmp_gt_i32_e32 vcc, v14, v44
	v_or_b32_e32 v44, 3, v62
	v_cmp_ne_u32_e64 s[6:7], v15, v44
	v_pk_mul_f32 v[42:43], v[64:65], v[56:57] op_sel_hi:[0,1]
	v_add_u32_e32 v63, 0xc0, v184
	v_cndmask_b32_e64 v41, v237, v41, s[6:7]
	v_cmp_gt_i32_e64 s[6:7], v15, v44
	ds_read_b128 v[158:161], v212
	ds_read_b128 v[44:47], v213
	v_cndmask_b32_e64 v165, v41, v43, s[6:7]
	v_cndmask_b32_e32 v164, v40, v42, vcc
	v_or_b32_e32 v52, 2, v63
	s_nop 0
	s_waitcnt lgkmcnt(2)
	v_pk_mul_f32 v[42:43], v[64:65], v[50:51] op_sel_hi:[0,1]
	v_or_b32_e32 v50, 3, v63
	s_nop 0
	s_waitcnt lgkmcnt(1)
	v_pk_mul_f32 v[40:41], v[170:171], v[160:161] op_sel_hi:[0,1]
	v_cmp_ne_u32_e32 vcc, v18, v52
	v_cmp_ne_u32_e64 s[6:7], v19, v50
	v_add_u32_e32 v250, 0xd0, v184
	v_cndmask_b32_e32 v40, v237, v40, vcc
	v_cmp_gt_i32_e32 vcc, v18, v52
	v_cndmask_b32_e64 v41, v237, v41, s[6:7]
	v_cmp_gt_i32_e64 s[6:7], v19, v50
	v_cndmask_b32_e32 v160, v40, v42, vcc
	v_or_b32_e32 v52, 2, v250
	v_cndmask_b32_e64 v161, v41, v43, s[6:7]
	ds_read_b128 v[56:59], v214
	ds_read_b128 v[40:43], v215
	v_cmp_ne_u32_e32 vcc, v22, v52
	s_nop 0
	s_waitcnt lgkmcnt(2)
	v_pk_mul_f32 v[46:47], v[64:65], v[46:47] op_sel_hi:[0,1]
	v_add_u32_e32 v251, 0xe0, v184
	s_nop 0
	s_waitcnt lgkmcnt(1)
	v_pk_mul_f32 v[50:51], v[170:171], v[58:59] op_sel_hi:[0,1]
	v_cndmask_b32_e32 v50, v237, v50, vcc
	v_cmp_gt_i32_e32 vcc, v22, v52
	v_or_b32_e32 v52, 3, v250
	v_cmp_ne_u32_e64 s[6:7], v23, v52
	v_cndmask_b32_e32 v46, v50, v46, vcc
	v_or_b32_e32 v58, 2, v251
	v_cndmask_b32_e64 v51, v237, v51, s[6:7]
	v_cmp_gt_i32_e64 s[6:7], v23, v52
	v_cmp_ne_u32_e32 vcc, v26, v58
	v_add_u32_e32 v252, 0xf0, v184
	v_cndmask_b32_e64 v47, v51, v47, s[6:7]
	ds_read_b128 v[50:53], v216
	ds_read_b128 v[246:249], v217
	s_nop 0
	s_waitcnt lgkmcnt(2)
	v_pk_mul_f32 v[42:43], v[64:65], v[42:43] op_sel_hi:[0,1]
	v_pk_mul_f32 v[38:39], v[170:171], v[38:39] op_sel_hi:[0,1]
	v_pk_mul_f32 v[32:33], v[170:171], v[32:33] op_sel_hi:[0,1]
	s_nop 0
	s_waitcnt lgkmcnt(1)
	v_pk_mul_f32 v[52:53], v[170:171], v[52:53] op_sel_hi:[0,1]
	v_cndmask_b32_e32 v52, v237, v52, vcc
	v_cmp_gt_i32_e32 vcc, v26, v58
	v_or_b32_e32 v58, 3, v251
	v_cmp_ne_u32_e64 s[6:7], v27, v58
	v_cndmask_b32_e32 v42, v52, v42, vcc
	v_pk_mul_f32 v[48:49], v[64:65], v[48:49] op_sel_hi:[0,1]
	v_cndmask_b32_e64 v53, v237, v53, s[6:7]
	v_cmp_gt_i32_e64 s[6:7], v27, v58
	v_or_b32_e32 v58, 2, v252
	v_cmp_ne_u32_e32 vcc, v30, v58
	v_cndmask_b32_e64 v43, v53, v43, s[6:7]
	s_nop 0
	s_waitcnt lgkmcnt(0)
	v_pk_mul_f32 v[52:53], v[64:65], v[248:249] op_sel_hi:[0,1]
	v_cndmask_b32_e32 v38, v237, v38, vcc
	v_cmp_gt_i32_e32 vcc, v30, v58
	v_or_b32_e32 v58, 3, v252
	v_cmp_ne_u32_e64 s[6:7], v31, v58
	v_cndmask_b32_e32 v38, v38, v52, vcc
	v_cmp_ne_u32_e32 vcc, v0, v185
	v_cndmask_b32_e64 v39, v237, v39, s[6:7]
	v_cmp_gt_i32_e64 s[6:7], v31, v58
	v_add_u32_e32 v58, 0x81, v184
	v_cndmask_b32_e32 v32, v237, v32, vcc
	v_cndmask_b32_e64 v39, v39, v53, s[6:7]
	v_cmp_ne_u32_e64 s[6:7], v1, v58
	v_pk_mul_f32 v[52:53], v[64:65], v[240:241] op_sel_hi:[0,1]
	v_cmp_gt_i32_e32 vcc, v0, v185
	v_cndmask_b32_e64 v33, v237, v33, s[6:7]
	v_cmp_gt_i32_e64 s[6:7], v1, v58
	v_cndmask_b32_e32 v32, v32, v52, vcc
	v_pk_mul_f32 v[58:59], v[170:171], v[242:243] op_sel_hi:[0,1]
	v_cndmask_b32_e64 v33, v33, v53, s[6:7]
	v_pk_mul_f32 v[52:53], v[64:65], v[166:167] op_sel_hi:[0,1]
	v_add_u32_e32 v166, 0x91, v184
	v_cmp_ne_u32_e32 vcc, v4, v225
	v_cmp_ne_u32_e64 s[6:7], v5, v166
	v_pk_mul_f32 v[44:45], v[64:65], v[44:45] op_sel_hi:[0,1]
	v_cndmask_b32_e32 v58, v237, v58, vcc
	v_cmp_gt_i32_e32 vcc, v4, v225
	v_cndmask_b32_e64 v59, v237, v59, s[6:7]
	v_cmp_gt_i32_e64 s[6:7], v5, v166
	v_cndmask_b32_e32 v166, v58, v52, vcc
	v_cmp_ne_u32_e32 vcc, v8, v226
	v_cndmask_b32_e64 v167, v59, v53, s[6:7]
	v_pk_mul_f32 v[52:53], v[64:65], v[60:61] op_sel_hi:[0,1]
	v_add_u32_e32 v60, 0xa1, v184
	v_pk_mul_f32 v[58:59], v[170:171], v[244:245] op_sel_hi:[0,1]
	v_cmp_ne_u32_e64 s[6:7], v9, v60
	v_cndmask_b32_e32 v58, v237, v58, vcc
	v_cmp_gt_i32_e32 vcc, v8, v226
	v_cndmask_b32_e64 v59, v237, v59, s[6:7]
	v_cmp_gt_i32_e64 s[6:7], v9, v60
	v_cndmask_b32_e32 v226, v58, v52, vcc
	v_cmp_ne_u32_e32 vcc, v12, v62
	v_cndmask_b32_e64 v227, v59, v53, s[6:7]
	v_pk_mul_f32 v[52:53], v[64:65], v[54:55] op_sel_hi:[0,1]
	v_pk_mul_f32 v[54:55], v[170:171], v[162:163] op_sel_hi:[0,1]
	v_add_u32_e32 v58, 0xb1, v184
	v_cndmask_b32_e32 v54, v237, v54, vcc
	v_cmp_gt_i32_e32 vcc, v12, v62
	v_cmp_ne_u32_e64 s[6:7], v13, v58
	v_pk_mul_f32 v[50:51], v[170:171], v[50:51] op_sel_hi:[0,1]
	v_cndmask_b32_e32 v162, v54, v52, vcc
	v_cndmask_b32_e64 v55, v237, v55, s[6:7]
	v_cmp_gt_i32_e64 s[6:7], v13, v58
	v_add_u32_e32 v54, 0xc1, v184
	v_cmp_ne_u32_e32 vcc, v16, v63
	v_cndmask_b32_e64 v163, v55, v53, s[6:7]
	v_pk_mul_f32 v[52:53], v[170:171], v[158:159] op_sel_hi:[0,1]
	v_cmp_ne_u32_e64 s[6:7], v17, v54
	v_cndmask_b32_e32 v52, v237, v52, vcc
	v_cmp_gt_i32_e32 vcc, v16, v63
	v_cndmask_b32_e64 v53, v237, v53, s[6:7]
	v_cmp_gt_i32_e64 s[6:7], v17, v54
	v_cndmask_b32_e32 v48, v52, v48, vcc
	v_cmp_ne_u32_e32 vcc, v20, v250
	v_cndmask_b32_e64 v49, v53, v49, s[6:7]
	v_pk_mul_f32 v[52:53], v[170:171], v[56:57] op_sel_hi:[0,1]
	v_add_u32_e32 v54, 0xd1, v184
	v_cndmask_b32_e32 v52, v237, v52, vcc
	v_cmp_gt_i32_e32 vcc, v20, v250
	v_cmp_ne_u32_e64 s[6:7], v21, v54
	v_pk_mul_f32 v[40:41], v[64:65], v[40:41] op_sel_hi:[0,1]
	v_cndmask_b32_e32 v44, v52, v44, vcc
	v_cndmask_b32_e64 v53, v237, v53, s[6:7]
	v_cmp_gt_i32_e64 s[6:7], v21, v54
	v_add_u32_e32 v52, 0xe1, v184
	v_cmp_ne_u32_e32 vcc, v24, v251
	v_cndmask_b32_e64 v45, v53, v45, s[6:7]
	v_cmp_ne_u32_e64 s[6:7], v25, v52
	v_cndmask_b32_e32 v50, v237, v50, vcc
	v_cmp_gt_i32_e32 vcc, v24, v251
	v_cndmask_b32_e64 v51, v237, v51, s[6:7]
	v_cmp_gt_i32_e64 s[6:7], v25, v52
	v_add_u32_e32 v52, 0xf1, v184
	v_cndmask_b32_e32 v40, v50, v40, vcc
	v_cndmask_b32_e64 v41, v51, v41, s[6:7]
	v_pk_mul_f32 v[36:37], v[170:171], v[36:37] op_sel_hi:[0,1]
	v_cmp_ne_u32_e32 vcc, v28, v252
	v_cmp_ne_u32_e64 s[6:7], v29, v52
	v_pk_mul_f32 v[50:51], v[64:65], v[246:247] op_sel_hi:[0,1]
	v_cndmask_b32_e32 v36, v237, v36, vcc
	v_cmp_gt_i32_e32 vcc, v28, v252
	v_cndmask_b32_e64 v37, v237, v37, s[6:7]
	v_cmp_gt_i32_e64 s[6:7], v29, v52
	v_cndmask_b32_e32 v36, v36, v50, vcc
	v_pk_mul_f32 v[62:63], v[156:157], v[38:39]
	v_cndmask_b32_e64 v37, v37, v51, s[6:7]
	v_pk_mul_f32 v[58:59], v[152:153], v[42:43]
	v_pk_mul_f32 v[54:55], v[148:149], v[46:47]
	v_pk_mul_f32 v[50:51], v[144:145], v[160:161]
	v_pk_mul_f32 v[46:47], v[124:125], v[164:165]
	v_pk_mul_f32 v[42:43], v[120:121], v[182:183]
	v_pk_mul_f32 v[38:39], v[116:117], v[168:169]
	v_pk_mul_f32 v[34:35], v[112:113], v[34:35]
	v_pk_mul_f32 v[60:61], v[154:155], v[36:37]
	v_pk_mul_f32 v[56:57], v[150:151], v[40:41]
	v_pk_mul_f32 v[52:53], v[146:147], v[44:45]
	v_pk_mul_f32 v[48:49], v[142:143], v[48:49]
	v_pk_mul_f32 v[44:45], v[122:123], v[162:163]
	v_pk_mul_f32 v[40:41], v[118:119], v[226:227]
	v_pk_mul_f32 v[36:37], v[114:115], v[166:167]
	v_pk_mul_f32 v[32:33], v[110:111], v[32:33]
	s_mov_b64 s[6:7], 0
.LBB0_1192:
	s_andn2_b64 vcc, exec, s[6:7]
	s_cbranch_vccnz .LBB0_1194
	s_waitcnt lgkmcnt(0)
	ds_read_b128 v[160:163], v171
	ds_read_b128 v[164:167], v171 offset:64
	ds_read_b128 v[240:243], v171 offset:128
	ds_read_b128 v[244:247], v171 offset:192
	ds_read_b128 v[248:251], v171 offset:256
	ds_read_b128 v[52:55], v171 offset:320
	ds_read_b128 v[56:59], v171 offset:384
	ds_read_b128 v[60:63], v171 offset:448
	s_nop 0
	s_waitcnt lgkmcnt(7)
	v_pk_mul_f32 v[34:35], v[170:171], v[162:163] op_sel_hi:[0,1]
	s_nop 0
	s_waitcnt lgkmcnt(6)
	v_pk_mul_f32 v[38:39], v[170:171], v[166:167] op_sel_hi:[0,1]
	s_nop 0
	s_waitcnt lgkmcnt(5)
	v_pk_mul_f32 v[42:43], v[170:171], v[242:243] op_sel_hi:[0,1]
	s_nop 0
	s_waitcnt lgkmcnt(4)
	v_pk_mul_f32 v[46:47], v[170:171], v[246:247] op_sel_hi:[0,1]
	s_nop 0
	s_waitcnt lgkmcnt(3)
	v_pk_mul_f32 v[50:51], v[170:171], v[250:251] op_sel_hi:[0,1]
	s_nop 0
	s_waitcnt lgkmcnt(2)
	v_pk_mul_f32 v[54:55], v[170:171], v[54:55] op_sel_hi:[0,1]
	s_nop 0
	s_waitcnt lgkmcnt(1)
	v_pk_mul_f32 v[58:59], v[170:171], v[58:59] op_sel_hi:[0,1]
	s_nop 0
	s_waitcnt lgkmcnt(0)
	v_pk_mul_f32 v[62:63], v[170:171], v[62:63] op_sel_hi:[0,1]
	v_pk_mul_f32 v[32:33], v[170:171], v[160:161] op_sel_hi:[0,1]
	v_pk_mul_f32 v[36:37], v[170:171], v[164:165] op_sel_hi:[0,1]
	v_pk_mul_f32 v[40:41], v[170:171], v[240:241] op_sel_hi:[0,1]
	v_pk_mul_f32 v[44:45], v[170:171], v[244:245] op_sel_hi:[0,1]
	v_pk_mul_f32 v[48:49], v[170:171], v[248:249] op_sel_hi:[0,1]
	v_pk_mul_f32 v[52:53], v[170:171], v[52:53] op_sel_hi:[0,1]
	v_pk_mul_f32 v[56:57], v[170:171], v[56:57] op_sel_hi:[0,1]
	v_pk_mul_f32 v[60:61], v[170:171], v[60:61] op_sel_hi:[0,1]
	v_pk_mul_f32 v[60:61], v[154:155], v[60:61]
	v_pk_mul_f32 v[56:57], v[150:151], v[56:57]
	v_pk_mul_f32 v[52:53], v[146:147], v[52:53]
	v_pk_mul_f32 v[48:49], v[142:143], v[48:49]
	v_pk_mul_f32 v[44:45], v[122:123], v[44:45]
	v_pk_mul_f32 v[40:41], v[118:119], v[40:41]
	v_pk_mul_f32 v[36:37], v[114:115], v[36:37]
	v_pk_mul_f32 v[32:33], v[110:111], v[32:33]
	v_pk_mul_f32 v[62:63], v[156:157], v[62:63]
	v_pk_mul_f32 v[58:59], v[152:153], v[58:59]
	v_pk_mul_f32 v[54:55], v[148:149], v[54:55]
	v_pk_mul_f32 v[50:51], v[144:145], v[50:51]
	v_pk_mul_f32 v[46:47], v[124:125], v[46:47]
	v_pk_mul_f32 v[42:43], v[120:121], v[42:43]
	v_pk_mul_f32 v[38:39], v[116:117], v[38:39]
	v_pk_mul_f32 v[34:35], v[112:113], v[34:35]

.LBB0_1195:
	s_andn2_b64 vcc, exec, s[6:7]
	s_cbranch_vccnz .LBB0_1153
	s_waitcnt lgkmcnt(0)
	v_add_u32_e32 v60, 0x12000, v202
	ds_read_b128 v[160:163], v60
	ds_read_b128 v[164:167], v60 offset:64
	ds_read_b128 v[168:171], v60 offset:128
	ds_read_b128 v[240:243], v60 offset:192
	ds_read_b128 v[244:247], v60 offset:256
	ds_read_b128 v[248:251], v60 offset:320
	s_nop 0
	s_nop 0
	s_nop 0
	s_nop 0
	s_nop 0
	s_nop 0
	s_nop 0
	ds_read_b128 v[56:59], v60 offset:384
	ds_read_b128 v[60:63], v60 offset:448
	s_nop 0
	s_waitcnt lgkmcnt(7)
	v_pk_mul_f32 v[34:35], v[64:65], v[162:163] op_sel_hi:[0,1]
	s_nop 0
	s_waitcnt lgkmcnt(6)
	v_pk_mul_f32 v[38:39], v[64:65], v[166:167] op_sel_hi:[0,1]
	s_nop 0
	s_waitcnt lgkmcnt(5)
	v_pk_mul_f32 v[42:43], v[64:65], v[170:171] op_sel_hi:[0,1]
	s_nop 0
	s_waitcnt lgkmcnt(4)
	v_pk_mul_f32 v[46:47], v[64:65], v[242:243] op_sel_hi:[0,1]
	s_nop 0
	s_waitcnt lgkmcnt(3)
	v_pk_mul_f32 v[50:51], v[64:65], v[246:247] op_sel_hi:[0,1]
	s_nop 0
	s_waitcnt lgkmcnt(2)
	v_pk_mul_f32 v[54:55], v[64:65], v[250:251] op_sel_hi:[0,1]
	s_nop 0
	s_waitcnt lgkmcnt(1)
	v_pk_mul_f32 v[58:59], v[64:65], v[58:59] op_sel_hi:[0,1]
	s_nop 0
	s_waitcnt lgkmcnt(0)
	v_pk_mul_f32 v[62:63], v[64:65], v[62:63] op_sel_hi:[0,1]
	v_pk_mul_f32 v[32:33], v[64:65], v[160:161] op_sel_hi:[0,1]
	v_pk_mul_f32 v[36:37], v[64:65], v[164:165] op_sel_hi:[0,1]
	v_pk_mul_f32 v[40:41], v[64:65], v[168:169] op_sel_hi:[0,1]
	v_pk_mul_f32 v[44:45], v[64:65], v[240:241] op_sel_hi:[0,1]
	v_pk_mul_f32 v[48:49], v[64:65], v[244:245] op_sel_hi:[0,1]
	v_pk_mul_f32 v[52:53], v[64:65], v[248:249] op_sel_hi:[0,1]
	v_pk_mul_f32 v[56:57], v[64:65], v[56:57] op_sel_hi:[0,1]
	v_pk_mul_f32 v[60:61], v[64:65], v[60:61] op_sel_hi:[0,1]
	v_pk_mul_f32 v[60:61], v[154:155], v[60:61]
	v_pk_mul_f32 v[56:57], v[150:151], v[56:57]
	v_pk_mul_f32 v[52:53], v[146:147], v[52:53]
	v_pk_mul_f32 v[48:49], v[142:143], v[48:49]
	v_pk_mul_f32 v[44:45], v[122:123], v[44:45]
	v_pk_mul_f32 v[40:41], v[118:119], v[40:41]
	v_pk_mul_f32 v[36:37], v[114:115], v[36:37]
	v_pk_mul_f32 v[32:33], v[110:111], v[32:33]
	v_pk_mul_f32 v[62:63], v[156:157], v[62:63]
	v_pk_mul_f32 v[58:59], v[152:153], v[58:59]
	v_pk_mul_f32 v[54:55], v[148:149], v[54:55]
	v_pk_mul_f32 v[50:51], v[144:145], v[50:51]
	v_pk_mul_f32 v[46:47], v[124:125], v[46:47]
	v_pk_mul_f32 v[42:43], v[120:121], v[42:43]
	v_pk_mul_f32 v[38:39], v[116:117], v[38:39]
	v_pk_mul_f32 v[34:35], v[112:113], v[34:35]
	s_branch .LBB0_1153
